# weight-conversion tile in scan phases: gain loads hoisted, data loads waited one by one, read-back reads issued together, cvt_pk packing
# baseline (speedup 1.0000x reference)
; #define GPTR(T, ptr) ((__attribute__((address_space(1))) T*)(ptr))
; __device__ __forceinline__ unsigned pack2(float a, float b) { return (unsigned)f2bf(a) | ((unsigned)f2bf(b) << 16); }
; __device__ void cvt_tile(const CvtJob& c, int tile, bfu* wt, const int tid_) {
;     ...
;   __syncthreads();
;   { _Pragma("unroll") for (int i = 0; i < 4; ++i) { const int idx = tid + 512 * i;
;       const int ch = ((idx >> 6) & 3) * 8 + (idx & 7), n = (idx >> 8) * 8 + ((idx >> 3) & 7);
;       u32x4 o_;
;       _Pragma("unroll") for (int e = 0; e < 4; ++e) o_[e] = pack2(ts[(ch * 8 + 2 * e) * 65 + n], ts[(ch * 8 + 2 * e + 1) * 65 + n]);
;       *GPTR(u32x4, wt + c.dst + (long)(n0 + n) * c.K + k0 + ch * 8) = o_; } }
.Lcvt_tail:
	v_lshrrev_b32_e32 v10, 3, v56
	v_and_b32_e32 v0, 7, v53
	v_and_or_b32 v11, v10, 24, v0
	v_ashrrev_i32_e32 v2, 5, v56
	v_mul_u32_u24_e32 v0, 0x208, v11
	v_bfi_b32 v8, -8, v2, v10
	v_lshlrev_b32_e32 v4, 2, v8
	v_lshlrev_b32_e32 v12, 2, v0
	v_add_u32_e32 v84, v4, v12
	v_add_u32_e32 v85, 0x410, v84
	s_waitcnt lgkmcnt(0)
	s_barrier
	ds_read2_b32 v[86:87], v84 offset0:0 offset1:130
	ds_read2_b32 v[88:89], v84 offset0:65 offset1:195
	ds_read2_b32 v[90:91], v85 offset0:0 offset1:130
	ds_read2_b32 v[92:93], v85 offset0:65 offset1:195
	ds_read2_b32 v[94:95], v84 offset0:16 offset1:146
	ds_read2_b32 v[96:97], v84 offset0:81 offset1:211
	ds_read2_b32 v[98:99], v85 offset0:16 offset1:146
	ds_read2_b32 v[100:101], v85 offset0:81 offset1:211
	ds_read2_b32 v[102:103], v84 offset0:32 offset1:162
	ds_read2_b32 v[104:105], v84 offset0:97 offset1:227
	ds_read2_b32 v[106:107], v85 offset0:32 offset1:162
	ds_read2_b32 v[108:109], v85 offset0:97 offset1:227
	ds_read2_b32 v[110:111], v84 offset0:48 offset1:178
	ds_read2_b32 v[112:113], v84 offset0:113 offset1:243
	ds_read2_b32 v[114:115], v85 offset0:48 offset1:178
	ds_read2_b32 v[116:117], v85 offset0:113 offset1:243
	s_mul_i32 s0, s27, s93
	s_add_i32 s0, s2, s0
	s_ashr_i32 s1, s0, 31
	s_lshl_b64 s[0:1], s[0:1], 1
	v_add_u32_e32 v6, s92, v8
	v_ashrrev_i32_e32 v9, 31, v6
	v_mad_u64_u32 v[6:7], s[14:15], v6, s68, 0
	v_mov_b32_e32 v8, v7
	v_mad_u64_u32 v[8:9], s[14:15], v9, s68, v[8:9]
	v_mov_b32_e32 v7, v8
	v_lshl_add_u64 v[6:7], v[6:7], 1, s[34:35]
	v_lshl_add_u64 v[6:7], v[6:7], 0, s[0:1]
	v_lshlrev_b32_e32 v0, 4, v11
	v_lshl_add_u64 v[118:119], v[6:7], 0, v[0:1]
	s_lshl_b32 s14, s68, 5
	s_mov_b32 s15, 0
	v_lshl_add_u64 v[120:121], v[118:119], 0, s[14:15]
	v_lshl_add_u64 v[122:123], v[120:121], 0, s[14:15]
	v_lshl_add_u64 v[124:125], v[122:123], 0, s[14:15]
	s_waitcnt lgkmcnt(12)
	v_cvt_pk_bf16_f32 v126, v86, v88
	v_cvt_pk_bf16_f32 v127, v87, v89
	v_cvt_pk_bf16_f32 v128, v90, v92
	v_cvt_pk_bf16_f32 v129, v91, v93
	global_store_dwordx4 v[118:119], v[126:129], off
	s_waitcnt lgkmcnt(8)
	v_cvt_pk_bf16_f32 v130, v94, v96
	v_cvt_pk_bf16_f32 v131, v95, v97
	v_cvt_pk_bf16_f32 v132, v98, v100
	v_cvt_pk_bf16_f32 v133, v99, v101
	global_store_dwordx4 v[120:121], v[130:133], off
	s_waitcnt lgkmcnt(4)
	v_cvt_pk_bf16_f32 v134, v102, v104
	v_cvt_pk_bf16_f32 v135, v103, v105
	v_cvt_pk_bf16_f32 v136, v106, v108
	v_cvt_pk_bf16_f32 v137, v107, v109
	global_store_dwordx4 v[122:123], v[134:137], off
	s_waitcnt lgkmcnt(0)
	v_cvt_pk_bf16_f32 v138, v110, v112
	v_cvt_pk_bf16_f32 v139, v111, v113
	v_cvt_pk_bf16_f32 v140, v114, v116
	v_cvt_pk_bf16_f32 v141, v115, v117
	global_store_dwordx4 v[124:125], v[138:141], off
	s_add_i32 s97, s97, s62
	s_add_i32 s2, s2, s3
	s_cmp_ge_i32 s97, s96
	s_cbranch_scc1 .LBB0_345

; #define GPTR(T, ptr) ((__attribute__((address_space(1))) T*)(ptr))
; __device__ void cvt_tile(const CvtJob& c, int tile, bfu* wt, const int tid_) {
;     ...
;   const int tid = tid_;
;   __syncthreads();
;   { f32x4 v[8];
;     _Pragma("unroll") for (int i = 0; i < 8; ++i) { const int idx = tid + 512 * i; const int kk = idx >> 4, n4 = idx & 15;
;       v[i] = *GPTR(const f32x4, src + (long)(k0 + kk) * c.ld + l0 + n4 * 4); }
;     _Pragma("unroll") for (int i = 0; i < 8; ++i) { const int idx = tid + 512 * i; const int kk = idx >> 4, n4 = idx & 15;
;       const float gsc = c.gain ? c.gain[k0 + kk] : 1.0f;
;       _Pragma("unroll") for (int e = 0; e < 4; ++e) ts[kk * 65 + n4 * 4 + e] = v[i][e] * gsc; } }
.LBB0_329:
	s_ashr_i32 s1, s0, 31
	s_lshl_b64 s[0:1], s[0:1], 2
	v_lshlrev_b32_e32 v0, 2, v53
	v_or_b32_e32 v56, s33, v53
	s_add_u32 s0, s14, s0
	v_and_b32_e32 v64, 60, v0
	s_addc_u32 s1, s15, s1
	v_lshlrev_b32_e32 v0, 2, v64
	v_ashrrev_i32_e32 v65, 4, v56
	s_mul_i32 s14, s26, s93
	s_waitcnt lgkmcnt(0)
	v_lshl_add_u64 v[2:3], s[0:1], 0, v[0:1]
	v_subrev_u32_e32 v0, s14, v65
	v_add_u32_e32 v48, s2, v0
	v_ashrrev_i32_e32 v49, 31, v48
	v_add_u32_e32 v55, 0x200, v56
	v_mul_lo_u32 v0, s36, v49
	v_mul_lo_u32 v6, s37, v48
	v_mad_u64_u32 v[4:5], s[0:1], s36, v48, 0
	v_ashrrev_i32_e32 v63, 4, v55
	v_add3_u32 v5, v5, v0, v6
	v_subrev_u32_e32 v0, s14, v63
	v_add_u32_e32 v46, s2, v0
	v_ashrrev_i32_e32 v47, 31, v46
	v_add_u32_e32 v54, 0x400, v56
	v_mul_lo_u32 v0, s36, v47
	v_mul_lo_u32 v8, s37, v46
	v_mad_u64_u32 v[6:7], s[0:1], s36, v46, 0
	v_ashrrev_i32_e32 v62, 4, v54
	v_add3_u32 v7, v7, v0, v8
	v_subrev_u32_e32 v0, s14, v62
	v_add_u32_e32 v44, s2, v0
	v_lshl_add_u64 v[4:5], v[4:5], 2, v[2:3]
	v_lshl_add_u64 v[6:7], v[6:7], 2, v[2:3]
	v_ashrrev_i32_e32 v45, 31, v44
	v_add_u32_e32 v51, 0x600, v56
	s_barrier
	v_mov_b32_e32 v66, 1.0
	v_mov_b32_e32 v68, 1.0
	v_mov_b32_e32 v70, 1.0
	v_mov_b32_e32 v72, 1.0
	v_mov_b32_e32 v74, 1.0
	v_mov_b32_e32 v76, 1.0
	v_mov_b32_e32 v78, 1.0
	v_mov_b32_e32 v80, 1.0
	s_andn2_b64 vcc, exec, s[28:29]
	s_cbranch_vccnz .Lcvt_nogain
	v_lshlrev_b32_e32 v82, 2, v48
	global_load_dword v66, v82, s[18:19]
	global_load_dword v68, v82, s[18:19] offset:128
	global_load_dword v70, v82, s[18:19] offset:256
	global_load_dword v72, v82, s[18:19] offset:384
	global_load_dword v74, v82, s[18:19] offset:512
	global_load_dword v76, v82, s[18:19] offset:640
	global_load_dword v78, v82, s[18:19] offset:768
	global_load_dword v80, v82, s[18:19] offset:896
.Lcvt_nogain:
	global_load_dwordx4 v[30:33], v[4:5], off
	global_load_dwordx4 v[18:21], v[6:7], off
	v_mul_lo_u32 v0, s36, v45
	v_mul_lo_u32 v6, s37, v44
	v_mad_u64_u32 v[4:5], s[0:1], s36, v44, 0
	v_ashrrev_i32_e32 v61, 4, v51
	v_add3_u32 v5, v5, v0, v6
	v_subrev_u32_e32 v0, s14, v61
	v_add_u32_e32 v42, s2, v0
	v_ashrrev_i32_e32 v43, 31, v42
	v_mul_lo_u32 v0, s36, v43
	v_mul_lo_u32 v8, s37, v42
	v_mad_u64_u32 v[6:7], s[0:1], s36, v42, 0
	v_add3_u32 v7, v7, v0, v8
	v_add_u32_e32 v0, 0x800, v56
	v_ashrrev_i32_e32 v60, 4, v0
	v_subrev_u32_e32 v0, s14, v60
	v_add_u32_e32 v40, s2, v0
	v_lshl_add_u64 v[4:5], v[4:5], 2, v[2:3]
	v_lshl_add_u64 v[6:7], v[6:7], 2, v[2:3]
	v_ashrrev_i32_e32 v41, 31, v40
	global_load_dwordx4 v[26:29], v[4:5], off
	global_load_dwordx4 v[10:13], v[6:7], off
	v_mul_lo_u32 v0, s36, v41
	v_mul_lo_u32 v6, s37, v40
	v_mad_u64_u32 v[4:5], s[0:1], s36, v40, 0
	v_add3_u32 v5, v5, v0, v6
	v_add_u32_e32 v0, 0xa00, v56
	v_ashrrev_i32_e32 v59, 4, v0
	v_subrev_u32_e32 v0, s14, v59
	v_add_u32_e32 v38, s2, v0
	v_ashrrev_i32_e32 v39, 31, v38
	v_mul_lo_u32 v0, s36, v39
	v_mul_lo_u32 v8, s37, v38
	v_mad_u64_u32 v[6:7], s[0:1], s36, v38, 0
	v_add3_u32 v7, v7, v0, v8
	v_add_u32_e32 v0, 0xc00, v56
	v_ashrrev_i32_e32 v58, 4, v0
	v_subrev_u32_e32 v0, s14, v58
	v_add_u32_e32 v36, s2, v0
	v_lshl_add_u64 v[4:5], v[4:5], 2, v[2:3]
	v_lshl_add_u64 v[6:7], v[6:7], 2, v[2:3]
	v_ashrrev_i32_e32 v37, 31, v36
	global_load_dwordx4 v[22:25], v[4:5], off
	s_nop 0
	global_load_dwordx4 v[6:9], v[6:7], off
	v_mul_lo_u32 v0, s36, v37
	v_mul_lo_u32 v14, s37, v36
	v_mad_u64_u32 v[4:5], s[0:1], s36, v36, 0
	v_add3_u32 v5, v5, v0, v14
	v_add_u32_e32 v0, 0xe00, v56
	v_ashrrev_i32_e32 v57, 4, v0
	v_subrev_u32_e32 v0, s14, v57
	v_add_u32_e32 v34, s2, v0
	v_ashrrev_i32_e32 v35, 31, v34
	v_mul_lo_u32 v0, s36, v35
	v_mul_lo_u32 v16, s37, v34
	v_mad_u64_u32 v[14:15], s[0:1], s36, v34, 0
	v_add3_u32 v15, v15, v0, v16
	v_lshl_add_u64 v[4:5], v[4:5], 2, v[2:3]
	v_lshl_add_u64 v[2:3], v[14:15], 2, v[2:3]
	global_load_dwordx4 v[14:17], v[4:5], off
	s_nop 0
	global_load_dwordx4 v[2:5], v[2:3], off
	v_lshl_add_u32 v0, v64, 2, 0
	v_mad_u32_u24 v83, v65, s75, v0
	s_waitcnt vmcnt(7)
	v_pk_mul_f32 v[30:31], v[30:31], v[66:67] op_sel_hi:[1,0]
	v_pk_mul_f32 v[32:33], v[32:33], v[66:67] op_sel_hi:[1,0]
	ds_write2_b32 v83, v30, v31 offset1:1
	ds_write2_b32 v83, v32, v33 offset0:2 offset1:3
	v_mad_u32_u24 v83, v63, s75, v0
	s_waitcnt vmcnt(6)
	v_pk_mul_f32 v[18:19], v[18:19], v[68:69] op_sel_hi:[1,0]
	v_pk_mul_f32 v[20:21], v[20:21], v[68:69] op_sel_hi:[1,0]
	ds_write2_b32 v83, v18, v19 offset1:1
	ds_write2_b32 v83, v20, v21 offset0:2 offset1:3
	v_mad_u32_u24 v83, v62, s75, v0
	s_waitcnt vmcnt(5)
	v_pk_mul_f32 v[26:27], v[26:27], v[70:71] op_sel_hi:[1,0]
	v_pk_mul_f32 v[28:29], v[28:29], v[70:71] op_sel_hi:[1,0]
	ds_write2_b32 v83, v26, v27 offset1:1
	ds_write2_b32 v83, v28, v29 offset0:2 offset1:3
	v_mad_u32_u24 v83, v61, s75, v0
	s_waitcnt vmcnt(4)
	v_pk_mul_f32 v[10:11], v[10:11], v[72:73] op_sel_hi:[1,0]
	v_pk_mul_f32 v[12:13], v[12:13], v[72:73] op_sel_hi:[1,0]
	ds_write2_b32 v83, v10, v11 offset1:1
	ds_write2_b32 v83, v12, v13 offset0:2 offset1:3
	v_mad_u32_u24 v83, v60, s75, v0
	s_waitcnt vmcnt(3)
	v_pk_mul_f32 v[22:23], v[22:23], v[74:75] op_sel_hi:[1,0]
	v_pk_mul_f32 v[24:25], v[24:25], v[74:75] op_sel_hi:[1,0]
	ds_write2_b32 v83, v22, v23 offset1:1
	ds_write2_b32 v83, v24, v25 offset0:2 offset1:3
	v_mad_u32_u24 v83, v59, s75, v0
	s_waitcnt vmcnt(2)
	v_pk_mul_f32 v[6:7], v[6:7], v[76:77] op_sel_hi:[1,0]
	v_pk_mul_f32 v[8:9], v[8:9], v[76:77] op_sel_hi:[1,0]
	ds_write2_b32 v83, v6, v7 offset1:1
	ds_write2_b32 v83, v8, v9 offset0:2 offset1:3
	v_mad_u32_u24 v83, v58, s75, v0
	s_waitcnt vmcnt(1)
	v_pk_mul_f32 v[14:15], v[14:15], v[78:79] op_sel_hi:[1,0]
	v_pk_mul_f32 v[16:17], v[16:17], v[78:79] op_sel_hi:[1,0]
	ds_write2_b32 v83, v14, v15 offset1:1
	ds_write2_b32 v83, v16, v17 offset0:2 offset1:3
	v_mad_u32_u24 v83, v57, s75, v0
	s_waitcnt vmcnt(0)
	v_pk_mul_f32 v[2:3], v[2:3], v[80:81] op_sel_hi:[1,0]
	v_pk_mul_f32 v[4:5], v[4:5], v[80:81] op_sel_hi:[1,0]
	ds_write2_b32 v83, v2, v3 offset1:1
	ds_write2_b32 v83, v4, v5 offset0:2 offset1:3
	s_branch .Lcvt_tail
